# hot loop heads (five GEMM K loops, attention main loop) pinned to 64-byte boundaries with .p2align 6
# speedup vs baseline: 1.0093x; 1.0023x over previous
;     __host__ __device__ bool next(int i, Unit& u) const { if (!S.next(i, u)) return false; if (u.pn >= skip0) u.pn += nskip; return true; }
; template <class Epi, class Sched, bool ALIGN_EPI = false, bool SP2 = false>
; __device__ __forceinline__ void gemm_phase(PG8_LAS unsigned char* lds, const Gemm g, const Sched& S, const Epi& E) {
;     ...
;         const bool has_next = S.next(ui + 1, nxt);
;         const char* nA = has_next ? (const char*)g.A + (size_t)nxt.pm * tstep : cA; const char* nB = has_next ? (const char*)g.Bt + (size_t)nxt.pn * tstep : cB;
;         for (int t = 0; t < nt; t += 2) {
;     ...
; #pragma unroll
;         for (int a = 0; a < 2; ++a)
; #pragma unroll
;             for (int b = 0; b < 2; ++b)
; #pragma unroll
;                 for (int m = 0; m < 4; ++m)
; #pragma unroll
;                     for (int n = 0; n < 2; ++n) acc[a][b][m][n] = (f32x4){0.f, 0.f, 0.f, 0.f};
;         cur = nxt; cA = nA; cB = nB; ++ui;
.LBB0_264:
	s_ashr_i32 s27, s26, 31
	s_lshl_b64 s[40:41], s[26:27], 20
	s_add_u32 s40, s28, s40
	s_addc_u32 s41, s46, s41
	s_and_b64 s[42:43], s[4:5], exec
	s_cselect_b32 s27, s41, s25
	s_cselect_b32 s59, s40, s24
	s_ashr_i32 s39, s38, 31
	s_lshl_b64 s[42:43], s[38:39], 20
	s_add_u32 s42, s47, s42
	s_addc_u32 s43, s48, s43
	s_and_b64 s[44:45], s[4:5], exec
	s_cselect_b32 s39, s43, s7
	s_cselect_b32 s60, s42, s6
	s_add_u32 s61, s6, 0x100
	s_addc_u32 s62, s7, 0
	s_add_u32 s6, s24, 0x80080
	v_mov_b32_e32 v0, 0
	s_addc_u32 s7, s25, 0
	s_mov_b32 s63, -2
	v_mov_b32_e32 v1, v0
	v_mov_b32_e32 v2, v0
	v_mov_b32_e32 v3, v0
	v_mov_b32_e32 v4, v0
	v_mov_b32_e32 v5, v0
	v_mov_b32_e32 v6, v0
	v_mov_b32_e32 v7, v0
	v_mov_b32_e32 v16, v0
	v_mov_b32_e32 v17, v0
	v_mov_b32_e32 v18, v0
	v_mov_b32_e32 v19, v0
	v_mov_b32_e32 v20, v0
	v_mov_b32_e32 v21, v0
	v_mov_b32_e32 v22, v0
	v_mov_b32_e32 v23, v0
	v_mov_b32_e32 v32, v0
	v_mov_b32_e32 v33, v0
	v_mov_b32_e32 v34, v0
	v_mov_b32_e32 v35, v0
	v_mov_b32_e32 v36, v0
	v_mov_b32_e32 v37, v0
	v_mov_b32_e32 v38, v0
	v_mov_b32_e32 v39, v0
	v_mov_b32_e32 v48, v0
	v_mov_b32_e32 v49, v0
	v_mov_b32_e32 v50, v0
	v_mov_b32_e32 v51, v0
	v_mov_b32_e32 v52, v0
	v_mov_b32_e32 v53, v0
	v_mov_b32_e32 v54, v0
	v_mov_b32_e32 v55, v0
	v_mov_b32_e32 v8, v0
	v_mov_b32_e32 v9, v0
	v_mov_b32_e32 v10, v0
	v_mov_b32_e32 v11, v0
	v_mov_b32_e32 v12, v0
	v_mov_b32_e32 v13, v0
	v_mov_b32_e32 v14, v0
	v_mov_b32_e32 v15, v0
	v_mov_b32_e32 v24, v0
	v_mov_b32_e32 v25, v0
	v_mov_b32_e32 v26, v0
	v_mov_b32_e32 v27, v0
	v_mov_b32_e32 v28, v0
	v_mov_b32_e32 v29, v0
	v_mov_b32_e32 v30, v0
	v_mov_b32_e32 v31, v0
	v_mov_b32_e32 v40, v0
	v_mov_b32_e32 v41, v0
	v_mov_b32_e32 v42, v0
	v_mov_b32_e32 v43, v0
	v_mov_b32_e32 v44, v0
	v_mov_b32_e32 v45, v0
	v_mov_b32_e32 v46, v0
	v_mov_b32_e32 v47, v0
	v_mov_b32_e32 v56, v0
	v_mov_b32_e32 v57, v0
	v_mov_b32_e32 v58, v0
	v_mov_b32_e32 v59, v0
	v_mov_b32_e32 v60, v0
	v_mov_b32_e32 v61, v0
	v_mov_b32_e32 v62, v0
	v_mov_b32_e32 v63, v0
	v_mov_b32_e32 v64, v0
	v_mov_b32_e32 v65, v0
	v_mov_b32_e32 v66, v0
	v_mov_b32_e32 v67, v0
	v_mov_b32_e32 v68, v0
	v_mov_b32_e32 v69, v0
	v_mov_b32_e32 v70, v0
	v_mov_b32_e32 v71, v0
	v_mov_b32_e32 v80, v0
	v_mov_b32_e32 v81, v0
	v_mov_b32_e32 v82, v0
	v_mov_b32_e32 v83, v0
	v_mov_b32_e32 v84, v0
	v_mov_b32_e32 v85, v0
	v_mov_b32_e32 v86, v0
	v_mov_b32_e32 v87, v0
	v_mov_b32_e32 v96, v0
	v_mov_b32_e32 v97, v0
	v_mov_b32_e32 v98, v0
	v_mov_b32_e32 v99, v0
	v_mov_b32_e32 v100, v0
	v_mov_b32_e32 v101, v0
	v_mov_b32_e32 v102, v0
	v_mov_b32_e32 v103, v0
	v_mov_b32_e32 v112, v0
	v_mov_b32_e32 v113, v0
	v_mov_b32_e32 v114, v0
	v_mov_b32_e32 v115, v0
	v_mov_b32_e32 v116, v0
	v_mov_b32_e32 v117, v0
	v_mov_b32_e32 v118, v0
	v_mov_b32_e32 v119, v0
	v_mov_b32_e32 v72, v0
	v_mov_b32_e32 v73, v0
	v_mov_b32_e32 v74, v0
	v_mov_b32_e32 v75, v0
	v_mov_b32_e32 v76, v0
	v_mov_b32_e32 v77, v0
	v_mov_b32_e32 v78, v0
	v_mov_b32_e32 v79, v0
	v_mov_b32_e32 v88, v0
	v_mov_b32_e32 v89, v0
	v_mov_b32_e32 v90, v0
	v_mov_b32_e32 v91, v0
	v_mov_b32_e32 v92, v0
	v_mov_b32_e32 v93, v0
	v_mov_b32_e32 v94, v0
	v_mov_b32_e32 v95, v0
	v_mov_b32_e32 v104, v0
	v_mov_b32_e32 v105, v0
	v_mov_b32_e32 v106, v0
	v_mov_b32_e32 v107, v0
	v_mov_b32_e32 v108, v0
	v_mov_b32_e32 v109, v0
	v_mov_b32_e32 v110, v0
	v_mov_b32_e32 v111, v0
	v_mov_b32_e32 v120, v0
	v_mov_b32_e32 v121, v0
	v_mov_b32_e32 v122, v0
	v_mov_b32_e32 v123, v0
	v_mov_b32_e32 v124, v0
	v_mov_b32_e32 v125, v0
	v_mov_b32_e32 v126, v0
	v_mov_b32_e32 v127, v0
	.p2align	6

;     __host__ __device__ bool next(int i, Unit& u) const { if (!S.next(i, u)) return false; if (u.pn >= skip0) u.pn += nskip; return true; }
; template <class Epi, class Sched, bool ALIGN_EPI = false, bool SP2 = false>
; __device__ __forceinline__ void gemm_phase(PG8_LAS unsigned char* lds, const Gemm g, const Sched& S, const Epi& E) {
;     ...
;         const bool has_next = S.next(ui + 1, nxt);
;         const char* nA = has_next ? (const char*)g.A + (size_t)nxt.pm * tstep : cA; const char* nB = has_next ? (const char*)g.Bt + (size_t)nxt.pn * tstep : cB;
;         for (int t = 0; t < nt; t += 2) {
;     ...
; #pragma unroll
;         for (int a = 0; a < 2; ++a)
; #pragma unroll
;             for (int b = 0; b < 2; ++b)
; #pragma unroll
;                 for (int m = 0; m < 4; ++m)
; #pragma unroll
;                     for (int n = 0; n < 2; ++n) acc[a][b][m][n] = (f32x4){0.f, 0.f, 0.f, 0.f};
;         cur = nxt; cA = nA; cB = nB; ++ui;
.LBB0_316:
	s_ashr_i32 s25, s24, 31
	s_lshl_b64 s[26:27], s[24:25], 20
	s_add_u32 s26, s47, s26
	s_addc_u32 s27, s48, s27
	s_and_b64 s[38:39], s[6:7], exec
	s_cselect_b32 s25, s27, s43
	s_cselect_b32 s59, s26, s42
	s_ashr_i32 s15, s14, 31
	s_lshl_b64 s[38:39], s[14:15], 20
	s_add_u32 s38, s28, s38
	s_addc_u32 s39, s46, s39
	s_and_b64 s[44:45], s[6:7], exec
	s_cselect_b32 s15, s39, s41
	s_cselect_b32 s60, s38, s40
	s_add_u32 s61, s40, 0x100
	s_addc_u32 s62, s41, 0
	s_add_u32 s40, s42, 0x80080
	v_mov_b32_e32 v0, 0
	s_addc_u32 s41, s43, 0
	s_mov_b32 s63, -2
	v_mov_b32_e32 v1, v0
	v_mov_b32_e32 v2, v0
	v_mov_b32_e32 v3, v0
	v_mov_b32_e32 v4, v0
	v_mov_b32_e32 v5, v0
	v_mov_b32_e32 v6, v0
	v_mov_b32_e32 v7, v0
	v_mov_b32_e32 v8, v0
	v_mov_b32_e32 v9, v0
	v_mov_b32_e32 v10, v0
	v_mov_b32_e32 v11, v0
	v_mov_b32_e32 v16, v0
	v_mov_b32_e32 v17, v0
	v_mov_b32_e32 v18, v0
	v_mov_b32_e32 v19, v0
	v_mov_b32_e32 v24, v0
	v_mov_b32_e32 v25, v0
	v_mov_b32_e32 v26, v0
	v_mov_b32_e32 v27, v0
	v_mov_b32_e32 v32, v0
	v_mov_b32_e32 v33, v0
	v_mov_b32_e32 v34, v0
	v_mov_b32_e32 v35, v0
	v_mov_b32_e32 v40, v0
	v_mov_b32_e32 v41, v0
	v_mov_b32_e32 v42, v0
	v_mov_b32_e32 v43, v0
	v_mov_b32_e32 v48, v0
	v_mov_b32_e32 v49, v0
	v_mov_b32_e32 v50, v0
	v_mov_b32_e32 v51, v0
	v_mov_b32_e32 v12, v0
	v_mov_b32_e32 v13, v0
	v_mov_b32_e32 v14, v0
	v_mov_b32_e32 v15, v0
	v_mov_b32_e32 v20, v0
	v_mov_b32_e32 v21, v0
	v_mov_b32_e32 v22, v0
	v_mov_b32_e32 v23, v0
	v_mov_b32_e32 v28, v0
	v_mov_b32_e32 v29, v0
	v_mov_b32_e32 v30, v0
	v_mov_b32_e32 v31, v0
	v_mov_b32_e32 v36, v0
	v_mov_b32_e32 v37, v0
	v_mov_b32_e32 v38, v0
	v_mov_b32_e32 v39, v0
	v_mov_b32_e32 v44, v0
	v_mov_b32_e32 v45, v0
	v_mov_b32_e32 v46, v0
	v_mov_b32_e32 v47, v0
	v_mov_b32_e32 v52, v0
	v_mov_b32_e32 v53, v0
	v_mov_b32_e32 v54, v0
	v_mov_b32_e32 v55, v0
	v_mov_b32_e32 v56, v0
	v_mov_b32_e32 v57, v0
	v_mov_b32_e32 v58, v0
	v_mov_b32_e32 v59, v0
	v_mov_b32_e32 v60, v0
	v_mov_b32_e32 v61, v0
	v_mov_b32_e32 v62, v0
	v_mov_b32_e32 v63, v0
	v_mov_b32_e32 v64, v0
	v_mov_b32_e32 v65, v0
	v_mov_b32_e32 v66, v0
	v_mov_b32_e32 v67, v0
	v_mov_b32_e32 v68, v0
	v_mov_b32_e32 v69, v0
	v_mov_b32_e32 v70, v0
	v_mov_b32_e32 v71, v0
	v_mov_b32_e32 v72, v0
	v_mov_b32_e32 v73, v0
	v_mov_b32_e32 v74, v0
	v_mov_b32_e32 v75, v0
	v_mov_b32_e32 v80, v0
	v_mov_b32_e32 v81, v0
	v_mov_b32_e32 v82, v0
	v_mov_b32_e32 v83, v0
	v_mov_b32_e32 v88, v0
	v_mov_b32_e32 v89, v0
	v_mov_b32_e32 v90, v0
	v_mov_b32_e32 v91, v0
	v_mov_b32_e32 v96, v0
	v_mov_b32_e32 v97, v0
	v_mov_b32_e32 v98, v0
	v_mov_b32_e32 v99, v0
	v_mov_b32_e32 v104, v0
	v_mov_b32_e32 v105, v0
	v_mov_b32_e32 v106, v0
	v_mov_b32_e32 v107, v0
	v_mov_b32_e32 v112, v0
	v_mov_b32_e32 v113, v0
	v_mov_b32_e32 v114, v0
	v_mov_b32_e32 v115, v0
	v_mov_b32_e32 v76, v0
	v_mov_b32_e32 v77, v0
	v_mov_b32_e32 v78, v0
	v_mov_b32_e32 v79, v0
	v_mov_b32_e32 v84, v0
	v_mov_b32_e32 v85, v0
	v_mov_b32_e32 v86, v0
	v_mov_b32_e32 v87, v0
	v_mov_b32_e32 v92, v0
	v_mov_b32_e32 v93, v0
	v_mov_b32_e32 v94, v0
	v_mov_b32_e32 v95, v0
	v_mov_b32_e32 v100, v0
	v_mov_b32_e32 v101, v0
	v_mov_b32_e32 v102, v0
	v_mov_b32_e32 v103, v0
	v_mov_b32_e32 v108, v0
	v_mov_b32_e32 v109, v0
	v_mov_b32_e32 v110, v0
	v_mov_b32_e32 v111, v0
	v_mov_b32_e32 v116, v0
	v_mov_b32_e32 v117, v0
	v_mov_b32_e32 v118, v0
	v_mov_b32_e32 v119, v0
	v_mov_b32_e32 v120, v0
	v_mov_b32_e32 v121, v0
	v_mov_b32_e32 v122, v0
	v_mov_b32_e32 v123, v0
	v_mov_b32_e32 v124, v0
	v_mov_b32_e32 v125, v0
	v_mov_b32_e32 v126, v0
	v_mov_b32_e32 v127, v0
	.p2align	6

;     __host__ __device__ bool next(int i, Unit& u) const { if (!S.next(i, u)) return false; if (u.pn >= skip0) u.pn += nskip; return true; }
; template <class Epi, class Sched, bool ALIGN_EPI = false, bool SP2 = false>
; __device__ __forceinline__ void gemm_phase(PG8_LAS unsigned char* lds, const Gemm g, const Sched& S, const Epi& E) {
;     ...
;         const bool has_next = S.next(ui + 1, nxt);
;         const char* nA = has_next ? (const char*)g.A + (size_t)nxt.pm * tstep : cA; const char* nB = has_next ? (const char*)g.Bt + (size_t)nxt.pn * tstep : cB;
;         for (int t = 0; t < nt; t += 2) {
;     ...
; #pragma unroll
;         for (int a = 0; a < 2; ++a)
; #pragma unroll
;             for (int b = 0; b < 2; ++b)
; #pragma unroll
;                 for (int m = 0; m < 4; ++m)
; #pragma unroll
;                     for (int n = 0; n < 2; ++n) acc[a][b][m][n] = (f32x4){0.f, 0.f, 0.f, 0.f};
;         cur = nxt; cA = nA; cB = nB; ++ui;
.LBB0_336:
	s_ashr_i32 s25, s24, 31
	s_lshl_b64 s[26:27], s[24:25], 17
	s_add_u32 s26, s28, s26
	s_addc_u32 s27, s56, s27
	s_and_b64 s[36:37], s[4:5], exec
	s_cselect_b32 s25, s27, s41
	s_cselect_b32 s69, s26, s40
	s_ashr_i32 s15, s14, 31
	s_lshl_b64 s[36:37], s[14:15], 17
	s_add_u32 s36, s57, s36
	s_addc_u32 s37, s58, s37
	s_and_b64 s[42:43], s[4:5], exec
	v_mov_b32_e32 v0, 0
	s_cselect_b32 s15, s37, s39
	s_cselect_b32 s70, s36, s38
	s_mov_b32 s46, 0
	s_mov_b64 s[42:43], -1
	s_mov_b64 s[44:45], 0
	v_mov_b32_e32 v1, v0
	v_mov_b32_e32 v2, v0
	v_mov_b32_e32 v3, v0
	v_mov_b32_e32 v4, v0
	v_mov_b32_e32 v5, v0
	v_mov_b32_e32 v6, v0
	v_mov_b32_e32 v7, v0
	v_mov_b32_e32 v8, v0
	v_mov_b32_e32 v9, v0
	v_mov_b32_e32 v10, v0
	v_mov_b32_e32 v11, v0
	v_mov_b32_e32 v16, v0
	v_mov_b32_e32 v17, v0
	v_mov_b32_e32 v18, v0
	v_mov_b32_e32 v19, v0
	v_mov_b32_e32 v24, v0
	v_mov_b32_e32 v25, v0
	v_mov_b32_e32 v26, v0
	v_mov_b32_e32 v27, v0
	v_mov_b32_e32 v32, v0
	v_mov_b32_e32 v33, v0
	v_mov_b32_e32 v34, v0
	v_mov_b32_e32 v35, v0
	v_mov_b32_e32 v40, v0
	v_mov_b32_e32 v41, v0
	v_mov_b32_e32 v42, v0
	v_mov_b32_e32 v43, v0
	v_mov_b32_e32 v48, v0
	v_mov_b32_e32 v49, v0
	v_mov_b32_e32 v50, v0
	v_mov_b32_e32 v51, v0
	v_mov_b32_e32 v12, v0
	v_mov_b32_e32 v13, v0
	v_mov_b32_e32 v14, v0
	v_mov_b32_e32 v15, v0
	v_mov_b32_e32 v20, v0
	v_mov_b32_e32 v21, v0
	v_mov_b32_e32 v22, v0
	v_mov_b32_e32 v23, v0
	v_mov_b32_e32 v28, v0
	v_mov_b32_e32 v29, v0
	v_mov_b32_e32 v30, v0
	v_mov_b32_e32 v31, v0
	v_mov_b32_e32 v36, v0
	v_mov_b32_e32 v37, v0
	v_mov_b32_e32 v38, v0
	v_mov_b32_e32 v39, v0
	v_mov_b32_e32 v44, v0
	v_mov_b32_e32 v45, v0
	v_mov_b32_e32 v46, v0
	v_mov_b32_e32 v47, v0
	v_mov_b32_e32 v52, v0
	v_mov_b32_e32 v53, v0
	v_mov_b32_e32 v54, v0
	v_mov_b32_e32 v55, v0
	v_mov_b32_e32 v56, v0
	v_mov_b32_e32 v57, v0
	v_mov_b32_e32 v58, v0
	v_mov_b32_e32 v59, v0
	v_mov_b32_e32 v60, v0
	v_mov_b32_e32 v61, v0
	v_mov_b32_e32 v62, v0
	v_mov_b32_e32 v63, v0
	v_mov_b32_e32 v64, v0
	v_mov_b32_e32 v65, v0
	v_mov_b32_e32 v66, v0
	v_mov_b32_e32 v67, v0
	v_mov_b32_e32 v68, v0
	v_mov_b32_e32 v69, v0
	v_mov_b32_e32 v70, v0
	v_mov_b32_e32 v71, v0
	v_mov_b32_e32 v72, v0
	v_mov_b32_e32 v73, v0
	v_mov_b32_e32 v74, v0
	v_mov_b32_e32 v75, v0
	v_mov_b32_e32 v80, v0
	v_mov_b32_e32 v81, v0
	v_mov_b32_e32 v82, v0
	v_mov_b32_e32 v83, v0
	v_mov_b32_e32 v88, v0
	v_mov_b32_e32 v89, v0
	v_mov_b32_e32 v90, v0
	v_mov_b32_e32 v91, v0
	v_mov_b32_e32 v96, v0
	v_mov_b32_e32 v97, v0
	v_mov_b32_e32 v98, v0
	v_mov_b32_e32 v99, v0
	v_mov_b32_e32 v104, v0
	v_mov_b32_e32 v105, v0
	v_mov_b32_e32 v106, v0
	v_mov_b32_e32 v107, v0
	v_mov_b32_e32 v112, v0
	v_mov_b32_e32 v113, v0
	v_mov_b32_e32 v114, v0
	v_mov_b32_e32 v115, v0
	v_mov_b32_e32 v76, v0
	v_mov_b32_e32 v77, v0
	v_mov_b32_e32 v78, v0
	v_mov_b32_e32 v79, v0
	v_mov_b32_e32 v84, v0
	v_mov_b32_e32 v85, v0
	v_mov_b32_e32 v86, v0
	v_mov_b32_e32 v87, v0
	v_mov_b32_e32 v92, v0
	v_mov_b32_e32 v93, v0
	v_mov_b32_e32 v94, v0
	v_mov_b32_e32 v95, v0
	v_mov_b32_e32 v100, v0
	v_mov_b32_e32 v101, v0
	v_mov_b32_e32 v102, v0
	v_mov_b32_e32 v103, v0
	v_mov_b32_e32 v108, v0
	v_mov_b32_e32 v109, v0
	v_mov_b32_e32 v110, v0
	v_mov_b32_e32 v111, v0
	v_mov_b32_e32 v116, v0
	v_mov_b32_e32 v117, v0
	v_mov_b32_e32 v118, v0
	v_mov_b32_e32 v119, v0
	v_mov_b32_e32 v120, v0
	v_mov_b32_e32 v121, v0
	v_mov_b32_e32 v122, v0
	v_mov_b32_e32 v123, v0
	v_mov_b32_e32 v124, v0
	v_mov_b32_e32 v125, v0
	v_mov_b32_e32 v126, v0
	v_mov_b32_e32 v127, v0
	.p2align	6

; #define ATT_LOAD(S, t) do { S[0] = *(const GAS v4u*)(gsrc[0] + (size_t)(t) * 64 * NH); S[1] = *(const GAS v4u*)(gsrc[1] + (size_t)(t) * 64 * NH); S[2] = *(const GAS v4u*)(gsrc[2] + (t) * 64); S[3] = *(const GAS v4u*)(gsrc[3] + (t) * 64); } while (0)
; #define ATT_STORE(S, boff) do { _Pragma("unroll") for (int i_ = 0; i_ < 2; ++i_) *(v4u*)(lds + (boff) + ldst[i_]) = S[i_]; \
;     _Pragma("unroll") for (int i_ = 2; i_ < 4; ++i_) { v2u lo_, hi_; lo_.x = S[i_].x; lo_.y = S[i_].y; hi_.x = S[i_].z; hi_.y = S[i_].w; *(v2u*)(lds + (boff) + ldst[i_]) = lo_; *(v2u*)(lds + (boff) + ldst[i_] + 16) = hi_; } } while (0)
; __device__ __forceinline__ void mix_attn(const bf16* h, const bf16* VT, const float* dl, int layer, const float* ng, bf16* ycat, char* lds, int wg, int G) {
;     ...
;             if (qb >= 1) ATT_STORE(stA, b1);
;             __syncthreads();
;             for (int t = 0; t < qb; ++t) {
;                 if (t + 2 <= qb) ATT_LOAD(stA, t + 2);
;                 if (t + 1 == qb) attn_step<true, true, true>(lds + b1 + st * K2OFF, lds + b0 + VOFF, qf, pf, oacc, mrun, lsum, true, rs, li, g);
;                 else attn_step<true, true, false>(lds + b1 + st * K2OFF, lds + b0 + VOFF, qf, pf, oacc, mrun, lsum, false, rs, li, g);
;                 if (t + 2 <= qb) ATT_STORE(stA, b2);
.LBB0_571:
	s_and_b64 vcc, exec, s[4:5]
	s_waitcnt lgkmcnt(0)
	s_barrier
	s_cbranch_vccnz .LBB0_582
	s_cmp_eq_u32 s79, 1
	s_cbranch_scc1 .LBB0_583
	s_add_i32 s15, s79, -1
	s_mov_b32 s78, 0x14000
	s_mov_b32 s14, 0xa000
	s_mov_b32 s81, 0
	s_movk_i32 s28, 0x80
	v_mov_b64_e32 v[32:33], v[176:177]
	v_mov_b64_e32 v[34:35], v[174:175]
	s_mov_b32 s80, 0
	s_lshl_b64 s[82:83], s[28:29], 1
	v_lshl_add_u64 v[36:37], v[186:187], 0, s[82:83]
	global_load_dwordx4 v[64:67], v[32:33], off
	global_load_dwordx4 v[68:71], v[34:35], off
	v_lshl_add_u64 v[38:39], v[188:189], 0, s[82:83]
	global_load_dwordx4 v[72:75], v[36:37], off
	global_load_dwordx4 v[76:79], v[38:39], off
	s_andn2_b64 vcc, exec, s[74:75]
	s_cbranch_vccnz .Lattn_stag_in
	s_barrier
	.p2align	6

;     __host__ __device__ bool next(int i, Unit& u) const { if (!S.next(i, u)) return false; if (u.pn >= skip0) u.pn += nskip; return true; }
; template <class Epi, class Sched, bool ALIGN_EPI = false, bool SP2 = false>
; __device__ __forceinline__ void gemm_phase(PG8_LAS unsigned char* lds, const Gemm g, const Sched& S, const Epi& E) {
;     ...
;         const bool has_next = S.next(ui + 1, nxt);
;         const char* nA = has_next ? (const char*)g.A + (size_t)nxt.pm * tstep : cA; const char* nB = has_next ? (const char*)g.Bt + (size_t)nxt.pn * tstep : cB;
;         for (int t = 0; t < nt; t += 2) {
;     ...
; #pragma unroll
;         for (int a = 0; a < 2; ++a)
; #pragma unroll
;             for (int b = 0; b < 2; ++b)
; #pragma unroll
;                 for (int m = 0; m < 4; ++m)
; #pragma unroll
;                     for (int n = 0; n < 2; ++n) acc[a][b][m][n] = (f32x4){0.f, 0.f, 0.f, 0.f};
;         cur = nxt; cA = nA; cB = nB; ++ui;
.LBB0_1132:
	s_ashr_i32 s51, s50, 31
	s_lshl_b64 s[14:15], s[50:51], 20
	s_add_u32 s52, s24, s14
	s_addc_u32 s53, s25, s15
	s_and_b64 s[14:15], s[42:43], exec
	s_cselect_b32 s51, s53, s3
	s_cselect_b32 s61, s52, s2
	s_ashr_i32 s49, s48, 31
	s_lshl_b64 s[14:15], s[48:49], 20
	s_add_u32 s54, s26, s14
	s_addc_u32 s55, s27, s15
	s_and_b64 s[14:15], s[42:43], exec
	s_cselect_b32 s49, s55, s1
	s_cselect_b32 s62, s54, s0
	s_add_u32 s63, s0, 0x100
	s_addc_u32 s64, s1, 0
	s_add_u32 s0, s2, 0x80080
	v_mov_b32_e32 v0, 0
	s_addc_u32 s1, s3, 0
	s_mov_b32 s65, -2
	v_mov_b32_e32 v1, v0
	v_mov_b32_e32 v2, v0
	v_mov_b32_e32 v3, v0
	v_mov_b32_e32 v4, v0
	v_mov_b32_e32 v5, v0
	v_mov_b32_e32 v6, v0
	v_mov_b32_e32 v7, v0
	v_mov_b32_e32 v16, v0
	v_mov_b32_e32 v17, v0
	v_mov_b32_e32 v18, v0
	v_mov_b32_e32 v19, v0
	v_mov_b32_e32 v20, v0
	v_mov_b32_e32 v21, v0
	v_mov_b32_e32 v22, v0
	v_mov_b32_e32 v23, v0
	v_mov_b32_e32 v32, v0
	v_mov_b32_e32 v33, v0
	v_mov_b32_e32 v34, v0
	v_mov_b32_e32 v35, v0
	v_mov_b32_e32 v36, v0
	v_mov_b32_e32 v37, v0
	v_mov_b32_e32 v38, v0
	v_mov_b32_e32 v39, v0
	v_mov_b32_e32 v48, v0
	v_mov_b32_e32 v49, v0
	v_mov_b32_e32 v50, v0
	v_mov_b32_e32 v51, v0
	v_mov_b32_e32 v52, v0
	v_mov_b32_e32 v53, v0
	v_mov_b32_e32 v54, v0
	v_mov_b32_e32 v55, v0
	v_mov_b32_e32 v8, v0
	v_mov_b32_e32 v9, v0
	v_mov_b32_e32 v10, v0
	v_mov_b32_e32 v11, v0
	v_mov_b32_e32 v12, v0
	v_mov_b32_e32 v13, v0
	v_mov_b32_e32 v14, v0
	v_mov_b32_e32 v15, v0
	v_mov_b32_e32 v24, v0
	v_mov_b32_e32 v25, v0
	v_mov_b32_e32 v26, v0
	v_mov_b32_e32 v27, v0
	v_mov_b32_e32 v28, v0
	v_mov_b32_e32 v29, v0
	v_mov_b32_e32 v30, v0
	v_mov_b32_e32 v31, v0
	v_mov_b32_e32 v40, v0
	v_mov_b32_e32 v41, v0
	v_mov_b32_e32 v42, v0
	v_mov_b32_e32 v43, v0
	v_mov_b32_e32 v44, v0
	v_mov_b32_e32 v45, v0
	v_mov_b32_e32 v46, v0
	v_mov_b32_e32 v47, v0
	v_mov_b32_e32 v56, v0
	v_mov_b32_e32 v57, v0
	v_mov_b32_e32 v58, v0
	v_mov_b32_e32 v59, v0
	v_mov_b32_e32 v60, v0
	v_mov_b32_e32 v61, v0
	v_mov_b32_e32 v62, v0
	v_mov_b32_e32 v63, v0
	v_mov_b32_e32 v64, v0
	v_mov_b32_e32 v65, v0
	v_mov_b32_e32 v66, v0
	v_mov_b32_e32 v67, v0
	v_mov_b32_e32 v68, v0
	v_mov_b32_e32 v69, v0
	v_mov_b32_e32 v70, v0
	v_mov_b32_e32 v71, v0
	v_mov_b32_e32 v80, v0
	v_mov_b32_e32 v81, v0
	v_mov_b32_e32 v82, v0
	v_mov_b32_e32 v83, v0
	v_mov_b32_e32 v84, v0
	v_mov_b32_e32 v85, v0
	v_mov_b32_e32 v86, v0
	v_mov_b32_e32 v87, v0
	v_mov_b32_e32 v96, v0
	v_mov_b32_e32 v97, v0
	v_mov_b32_e32 v98, v0
	v_mov_b32_e32 v99, v0
	v_mov_b32_e32 v100, v0
	v_mov_b32_e32 v101, v0
	v_mov_b32_e32 v102, v0
	v_mov_b32_e32 v103, v0
	v_mov_b32_e32 v112, v0
	v_mov_b32_e32 v113, v0
	v_mov_b32_e32 v114, v0
	v_mov_b32_e32 v115, v0
	v_mov_b32_e32 v116, v0
	v_mov_b32_e32 v117, v0
	v_mov_b32_e32 v118, v0
	v_mov_b32_e32 v119, v0
	v_mov_b32_e32 v72, v0
	v_mov_b32_e32 v73, v0
	v_mov_b32_e32 v74, v0
	v_mov_b32_e32 v75, v0
	v_mov_b32_e32 v76, v0
	v_mov_b32_e32 v77, v0
	v_mov_b32_e32 v78, v0
	v_mov_b32_e32 v79, v0
	v_mov_b32_e32 v88, v0
	v_mov_b32_e32 v89, v0
	v_mov_b32_e32 v90, v0
	v_mov_b32_e32 v91, v0
	v_mov_b32_e32 v92, v0
	v_mov_b32_e32 v93, v0
	v_mov_b32_e32 v94, v0
	v_mov_b32_e32 v95, v0
	v_mov_b32_e32 v104, v0
	v_mov_b32_e32 v105, v0
	v_mov_b32_e32 v106, v0
	v_mov_b32_e32 v107, v0
	v_mov_b32_e32 v108, v0
	v_mov_b32_e32 v109, v0
	v_mov_b32_e32 v110, v0
	v_mov_b32_e32 v111, v0
	v_mov_b32_e32 v120, v0
	v_mov_b32_e32 v121, v0
	v_mov_b32_e32 v122, v0
	v_mov_b32_e32 v123, v0
	v_mov_b32_e32 v124, v0
	v_mov_b32_e32 v125, v0
	v_mov_b32_e32 v126, v0
	v_mov_b32_e32 v127, v0
	.p2align	6

;     __host__ __device__ bool next(int i, Unit& u) const { if (!S.next(i, u)) return false; if (u.pn >= skip0) u.pn += nskip; return true; }
; template <class Epi, class Sched, bool ALIGN_EPI = false, bool SP2 = false>
; __device__ __forceinline__ void gemm_phase(PG8_LAS unsigned char* lds, const Gemm g, const Sched& S, const Epi& E) {
;     ...
;         const bool has_next = S.next(ui + 1, nxt);
;         const char* nA = has_next ? (const char*)g.A + (size_t)nxt.pm * tstep : cA; const char* nB = has_next ? (const char*)g.Bt + (size_t)nxt.pn * tstep : cB;
;         for (int t = 0; t < nt; t += 2) {
;     ...
; #pragma unroll
;         for (int a = 0; a < 2; ++a)
; #pragma unroll
;             for (int b = 0; b < 2; ++b)
; #pragma unroll
;                 for (int m = 0; m < 4; ++m)
; #pragma unroll
;                     for (int n = 0; n < 2; ++n) acc[a][b][m][n] = (f32x4){0.f, 0.f, 0.f, 0.f};
;         cur = nxt; cA = nA; cB = nB; ++ui;
.LBB0_1340:
	s_ashr_i32 s65, s64, 31
	s_lshl_b64 s[14:15], s[64:65], 20
	s_add_u32 s66, s82, s14
	s_addc_u32 s67, s83, s15
	s_and_b64 s[14:15], s[38:39], exec
	s_cselect_b32 s65, s67, s3
	s_cselect_b32 s73, s66, s2
	s_ashr_i32 s63, s62, 31
	s_lshl_b64 s[14:15], s[62:63], 20
	s_add_u32 s68, s24, s14
	s_addc_u32 s69, s25, s15
	s_and_b64 s[14:15], s[38:39], exec
	s_cselect_b32 s63, s69, s1
	s_cselect_b32 s74, s68, s0
	s_add_u32 s75, s0, 0x100
	s_addc_u32 s76, s1, 0
	s_add_u32 s0, s2, 0x80080
	v_mov_b32_e32 v0, 0
	s_addc_u32 s1, s3, 0
	s_mov_b32 s77, -2
	v_mov_b32_e32 v1, v0
	v_mov_b32_e32 v2, v0
	v_mov_b32_e32 v3, v0
	v_mov_b32_e32 v4, v0
	v_mov_b32_e32 v5, v0
	v_mov_b32_e32 v6, v0
	v_mov_b32_e32 v7, v0
	v_mov_b32_e32 v8, v0
	v_mov_b32_e32 v9, v0
	v_mov_b32_e32 v10, v0
	v_mov_b32_e32 v11, v0
	v_mov_b32_e32 v12, v0
	v_mov_b32_e32 v13, v0
	v_mov_b32_e32 v14, v0
	v_mov_b32_e32 v15, v0
	v_mov_b32_e32 v16, v0
	v_mov_b32_e32 v17, v0
	v_mov_b32_e32 v18, v0
	v_mov_b32_e32 v19, v0
	v_mov_b32_e32 v20, v0
	v_mov_b32_e32 v21, v0
	v_mov_b32_e32 v22, v0
	v_mov_b32_e32 v23, v0
	v_mov_b32_e32 v24, v0
	v_mov_b32_e32 v25, v0
	v_mov_b32_e32 v26, v0
	v_mov_b32_e32 v27, v0
	v_mov_b32_e32 v28, v0
	v_mov_b32_e32 v29, v0
	v_mov_b32_e32 v30, v0
	v_mov_b32_e32 v31, v0
	v_mov_b32_e32 v64, v0
	v_mov_b32_e32 v65, v0
	v_mov_b32_e32 v66, v0
	v_mov_b32_e32 v67, v0
	v_mov_b32_e32 v68, v0
	v_mov_b32_e32 v69, v0
	v_mov_b32_e32 v70, v0
	v_mov_b32_e32 v71, v0
	v_mov_b32_e32 v72, v0
	v_mov_b32_e32 v73, v0
	v_mov_b32_e32 v74, v0
	v_mov_b32_e32 v75, v0
	v_mov_b32_e32 v76, v0
	v_mov_b32_e32 v77, v0
	v_mov_b32_e32 v78, v0
	v_mov_b32_e32 v79, v0
	v_mov_b32_e32 v80, v0
	v_mov_b32_e32 v81, v0
	v_mov_b32_e32 v82, v0
	v_mov_b32_e32 v83, v0
	v_mov_b32_e32 v84, v0
	v_mov_b32_e32 v85, v0
	v_mov_b32_e32 v86, v0
	v_mov_b32_e32 v87, v0
	v_mov_b32_e32 v112, v0
	v_mov_b32_e32 v113, v0
	v_mov_b32_e32 v114, v0
	v_mov_b32_e32 v115, v0
	v_mov_b32_e32 v120, v0
	v_mov_b32_e32 v121, v0
	v_mov_b32_e32 v122, v0
	v_mov_b32_e32 v123, v0
	v_mov_b32_e32 v32, v0
	v_mov_b32_e32 v33, v0
	v_mov_b32_e32 v34, v0
	v_mov_b32_e32 v35, v0
	v_mov_b32_e32 v36, v0
	v_mov_b32_e32 v37, v0
	v_mov_b32_e32 v38, v0
	v_mov_b32_e32 v39, v0
	v_mov_b32_e32 v40, v0
	v_mov_b32_e32 v41, v0
	v_mov_b32_e32 v42, v0
	v_mov_b32_e32 v43, v0
	v_mov_b32_e32 v44, v0
	v_mov_b32_e32 v45, v0
	v_mov_b32_e32 v46, v0
	v_mov_b32_e32 v47, v0
	v_mov_b32_e32 v48, v0
	v_mov_b32_e32 v49, v0
	v_mov_b32_e32 v50, v0
	v_mov_b32_e32 v51, v0
	v_mov_b32_e32 v52, v0
	v_mov_b32_e32 v53, v0
	v_mov_b32_e32 v54, v0
	v_mov_b32_e32 v55, v0
	v_mov_b32_e32 v56, v0
	v_mov_b32_e32 v57, v0
	v_mov_b32_e32 v58, v0
	v_mov_b32_e32 v59, v0
	v_mov_b32_e32 v60, v0
	v_mov_b32_e32 v61, v0
	v_mov_b32_e32 v62, v0
	v_mov_b32_e32 v63, v0
	v_mov_b32_e32 v128, v0
	v_mov_b32_e32 v129, v0
	v_mov_b32_e32 v130, v0
	v_mov_b32_e32 v131, v0
	v_mov_b32_e32 v132, v0
	v_mov_b32_e32 v133, v0
	v_mov_b32_e32 v134, v0
	v_mov_b32_e32 v135, v0
	v_mov_b32_e32 v136, v0
	v_mov_b32_e32 v137, v0
	v_mov_b32_e32 v138, v0
	v_mov_b32_e32 v139, v0
	v_mov_b32_e32 v140, v0
	v_mov_b32_e32 v141, v0
	v_mov_b32_e32 v142, v0
	v_mov_b32_e32 v143, v0
	v_mov_b32_e32 v144, v0
	v_mov_b32_e32 v145, v0
	v_mov_b32_e32 v146, v0
	v_mov_b32_e32 v147, v0
	v_mov_b32_e32 v148, v0
	v_mov_b32_e32 v149, v0
	v_mov_b32_e32 v150, v0
	v_mov_b32_e32 v151, v0
	v_mov_b32_e32 v152, v0
	v_mov_b32_e32 v153, v0
	v_mov_b32_e32 v154, v0
	v_mov_b32_e32 v155, v0
	v_mov_b32_e32 v156, v0
	v_mov_b32_e32 v157, v0
	v_mov_b32_e32 v158, v0
	v_mov_b32_e32 v159, v0
	.p2align	6
